# final RMSNorm: 4 rows batched per trip with lane-contiguous stores, non-temporal input reads and output stores (on top of nt5)
# speedup vs baseline: 1.0069x; 1.0069x over previous
; __global__ void __launch_bounds__(NWAVES * 64, 2) mk_fwd(Args args) {
;     ...
;         for (int m = gw; m < MT; m += NGW) { const float rs = row_rstd(ss, m);
;             const u32x4* xr = (const u32x4*)(X3 + (size_t)m * DM) + lane; f32x4* orow = (f32x4*)(P.out + (size_t)m * DM); const f32x4* gr = (const f32x4*)P.g_fin;
; #pragma unroll
;             for (int j = 0; j < 2; ++j) { const u32x4 w = xr[64 * j]; const int c4 = (64 * j + lane) * 2; const f32x4 ga = gr[c4], gb = gr[c4 + 1];
;                 f32x4 a, b2; a[0] = bflo(w.x) * rs * ga[0]; a[1] = bfhi(w.x) * rs * ga[1]; a[2] = bflo(w.y) * rs * ga[2]; a[3] = bfhi(w.y) * rs * ga[3];
;                 b2[0] = bflo(w.z) * rs * gb[0]; b2[1] = bfhi(w.z) * rs * gb[1]; b2[2] = bflo(w.w) * rs * gb[2]; b2[3] = bfhi(w.w) * rs * gb[3];
;                 orow[c4] = a; orow[c4 + 1] = b2; } }
.Lp9_loop:
	s_mov_b32 s16, s8
	s_lshl_b32 s17, s16, 6
	s_add_u32 s18, s12, s17
	s_addc_u32 s19, s13, 0
	global_load_dwordx4 v[32:35], v2, s[18:19]
	global_load_dwordx4 v[36:39], v2, s[18:19] offset:16
	global_load_dwordx4 v[40:43], v2, s[18:19] offset:32
	global_load_dwordx4 v[44:47], v2, s[18:19] offset:48
	s_lshl_b32 s17, s16, 11
	s_add_u32 s18, s14, s17
	s_addc_u32 s19, s15, 0
	global_load_dwordx2 v[48:49], v1, s[18:19] nt
	global_load_dwordx2 v[50:51], v1, s[18:19] offset:512 nt
	global_load_dwordx2 v[52:53], v1, s[18:19] offset:1024 nt
	global_load_dwordx2 v[54:55], v1, s[18:19] offset:1536 nt
	s_add_i32 s16, s16, s58
	s_lshl_b32 s17, s16, 6
	s_add_u32 s18, s12, s17
	s_addc_u32 s19, s13, 0
	global_load_dwordx4 v[56:59], v2, s[18:19]
	global_load_dwordx4 v[60:63], v2, s[18:19] offset:16
	global_load_dwordx4 v[64:67], v2, s[18:19] offset:32
	global_load_dwordx4 v[68:71], v2, s[18:19] offset:48
	s_lshl_b32 s17, s16, 11
	s_add_u32 s18, s14, s17
	s_addc_u32 s19, s15, 0
	global_load_dwordx2 v[72:73], v1, s[18:19] nt
	global_load_dwordx2 v[74:75], v1, s[18:19] offset:512 nt
	global_load_dwordx2 v[76:77], v1, s[18:19] offset:1024 nt
	global_load_dwordx2 v[78:79], v1, s[18:19] offset:1536 nt
	s_add_i32 s16, s16, s58
	s_lshl_b32 s17, s16, 6
	s_add_u32 s18, s12, s17
	s_addc_u32 s19, s13, 0
	global_load_dwordx4 v[80:83], v2, s[18:19]
	global_load_dwordx4 v[84:87], v2, s[18:19] offset:16
	global_load_dwordx4 v[88:91], v2, s[18:19] offset:32
	global_load_dwordx4 v[92:95], v2, s[18:19] offset:48
	s_lshl_b32 s17, s16, 11
	s_add_u32 s18, s14, s17
	s_addc_u32 s19, s15, 0
	global_load_dwordx2 v[96:97], v1, s[18:19] nt
	global_load_dwordx2 v[98:99], v1, s[18:19] offset:512 nt
	global_load_dwordx2 v[100:101], v1, s[18:19] offset:1024 nt
	global_load_dwordx2 v[102:103], v1, s[18:19] offset:1536 nt
	s_add_i32 s16, s16, s58
	s_lshl_b32 s17, s16, 6
	s_add_u32 s18, s12, s17
	s_addc_u32 s19, s13, 0
	global_load_dwordx4 v[104:107], v2, s[18:19]
	global_load_dwordx4 v[108:111], v2, s[18:19] offset:16
	global_load_dwordx4 v[112:115], v2, s[18:19] offset:32
	global_load_dwordx4 v[116:119], v2, s[18:19] offset:48
	s_lshl_b32 s17, s16, 11
	s_add_u32 s18, s14, s17
	s_addc_u32 s19, s15, 0
	global_load_dwordx2 v[120:121], v1, s[18:19] nt
	global_load_dwordx2 v[122:123], v1, s[18:19] offset:512 nt
	global_load_dwordx2 v[124:125], v1, s[18:19] offset:1024 nt
	global_load_dwordx2 v[126:127], v1, s[18:19] offset:1536 nt
	s_mov_b32 s16, s8
	s_waitcnt vmcnt(24)
	v_add_f32_e32 v32, v32, v33
	v_add_f32_e32 v34, v34, v35
	v_add_f32_e32 v36, v36, v37
	v_add_f32_e32 v38, v38, v39
	v_add_f32_e32 v40, v40, v41
	v_add_f32_e32 v42, v42, v43
	v_add_f32_e32 v44, v44, v45
	v_add_f32_e32 v46, v46, v47
	v_add_f32_e32 v32, v32, v34
	v_add_f32_e32 v36, v36, v38
	v_add_f32_e32 v40, v40, v42
	v_add_f32_e32 v44, v44, v46
	v_add_f32_e32 v32, v32, v36
	v_add_f32_e32 v40, v40, v44
	v_add_f32_e32 v32, v32, v40
	v_fmamk_f32 v32, v32, 0x3a800000, v8
	v_rsq_f32_e32 v9, v32
	v_lshlrev_b32_e32 v128, 16, v48
	v_and_b32_e32 v129, 0xffff0000, v48
	v_lshlrev_b32_e32 v130, 16, v49
	v_and_b32_e32 v131, 0xffff0000, v49
	v_lshlrev_b32_e32 v132, 16, v50
	v_and_b32_e32 v133, 0xffff0000, v50
	v_lshlrev_b32_e32 v134, 16, v51
	v_and_b32_e32 v135, 0xffff0000, v51
	v_lshlrev_b32_e32 v136, 16, v52
	v_and_b32_e32 v137, 0xffff0000, v52
	v_lshlrev_b32_e32 v138, 16, v53
	v_and_b32_e32 v139, 0xffff0000, v53
	v_lshlrev_b32_e32 v140, 16, v54
	v_and_b32_e32 v141, 0xffff0000, v54
	v_lshlrev_b32_e32 v142, 16, v55
	v_and_b32_e32 v143, 0xffff0000, v55
	v_mul_f32_e32 v128, v9, v128
	v_mul_f32_e32 v129, v9, v129
	v_mul_f32_e32 v130, v9, v130
	v_mul_f32_e32 v131, v9, v131
	v_mul_f32_e32 v132, v9, v132
	v_mul_f32_e32 v133, v9, v133
	v_mul_f32_e32 v134, v9, v134
	v_mul_f32_e32 v135, v9, v135
	v_mul_f32_e32 v136, v9, v136
	v_mul_f32_e32 v137, v9, v137
	v_mul_f32_e32 v138, v9, v138
	v_mul_f32_e32 v139, v9, v139
	v_mul_f32_e32 v140, v9, v140
	v_mul_f32_e32 v141, v9, v141
	v_mul_f32_e32 v142, v9, v142
	v_mul_f32_e32 v143, v9, v143
	v_mul_f32_e32 v128, v10, v128
	v_mul_f32_e32 v129, v11, v129
	v_mul_f32_e32 v130, v12, v130
	v_mul_f32_e32 v131, v13, v131
	v_mul_f32_e32 v132, v14, v132
	v_mul_f32_e32 v133, v15, v133
	v_mul_f32_e32 v134, v16, v134
	v_mul_f32_e32 v135, v17, v135
	v_mul_f32_e32 v136, v18, v136
	v_mul_f32_e32 v137, v19, v137
	v_mul_f32_e32 v138, v20, v138
	v_mul_f32_e32 v139, v21, v139
	v_mul_f32_e32 v140, v22, v140
	v_mul_f32_e32 v141, v23, v141
	v_mul_f32_e32 v142, v24, v142
	v_mul_f32_e32 v143, v25, v143
	s_lshl_b32 s17, s16, 12
	s_add_u32 s18, s66, s17
	s_addc_u32 s19, s67, 0
	global_store_dwordx4 v0, v[128:131], s[18:19] nt
	global_store_dwordx4 v0, v[132:135], s[18:19] offset:1024 nt
	global_store_dwordx4 v0, v[136:139], s[18:19] offset:2048 nt
	global_store_dwordx4 v0, v[140:143], s[18:19] offset:3072 nt
	s_add_i32 s16, s16, s58
	s_waitcnt vmcnt(20)
; __global__ void __launch_bounds__(NWAVES * 64, 2) mk_fwd(Args args) {
;     ...
;         for (int m = gw; m < MT; m += NGW) { const float rs = row_rstd(ss, m);
;             const u32x4* xr = (const u32x4*)(X3 + (size_t)m * DM) + lane; f32x4* orow = (f32x4*)(P.out + (size_t)m * DM); const f32x4* gr = (const f32x4*)P.g_fin;
; #pragma unroll
;             for (int j = 0; j < 2; ++j) { const u32x4 w = xr[64 * j]; const int c4 = (64 * j + lane) * 2; const f32x4 ga = gr[c4], gb = gr[c4 + 1];
;                 f32x4 a, b2; a[0] = bflo(w.x) * rs * ga[0]; a[1] = bfhi(w.x) * rs * ga[1]; a[2] = bflo(w.y) * rs * ga[2]; a[3] = bfhi(w.y) * rs * ga[3];
;                 b2[0] = bflo(w.z) * rs * gb[0]; b2[1] = bfhi(w.z) * rs * gb[1]; b2[2] = bflo(w.w) * rs * gb[2]; b2[3] = bfhi(w.w) * rs * gb[3];
;                 orow[c4] = a; orow[c4 + 1] = b2; } }
	v_add_f32_e32 v56, v56, v57
	v_add_f32_e32 v58, v58, v59
	v_add_f32_e32 v60, v60, v61
	v_add_f32_e32 v62, v62, v63
	v_add_f32_e32 v64, v64, v65
	v_add_f32_e32 v66, v66, v67
	v_add_f32_e32 v68, v68, v69
	v_add_f32_e32 v70, v70, v71
	v_add_f32_e32 v56, v56, v58
	v_add_f32_e32 v60, v60, v62
	v_add_f32_e32 v64, v64, v66
	v_add_f32_e32 v68, v68, v70
	v_add_f32_e32 v56, v56, v60
	v_add_f32_e32 v64, v64, v68
	v_add_f32_e32 v56, v56, v64
	v_fmamk_f32 v56, v56, 0x3a800000, v8
	v_rsq_f32_e32 v9, v56
	v_lshlrev_b32_e32 v128, 16, v72
	v_and_b32_e32 v129, 0xffff0000, v72
	v_lshlrev_b32_e32 v130, 16, v73
	v_and_b32_e32 v131, 0xffff0000, v73
	v_lshlrev_b32_e32 v132, 16, v74
	v_and_b32_e32 v133, 0xffff0000, v74
	v_lshlrev_b32_e32 v134, 16, v75
	v_and_b32_e32 v135, 0xffff0000, v75
	v_lshlrev_b32_e32 v136, 16, v76
	v_and_b32_e32 v137, 0xffff0000, v76
	v_lshlrev_b32_e32 v138, 16, v77
	v_and_b32_e32 v139, 0xffff0000, v77
	v_lshlrev_b32_e32 v140, 16, v78
	v_and_b32_e32 v141, 0xffff0000, v78
	v_lshlrev_b32_e32 v142, 16, v79
	v_and_b32_e32 v143, 0xffff0000, v79
	v_mul_f32_e32 v128, v9, v128
	v_mul_f32_e32 v129, v9, v129
	v_mul_f32_e32 v130, v9, v130
	v_mul_f32_e32 v131, v9, v131
	v_mul_f32_e32 v132, v9, v132
	v_mul_f32_e32 v133, v9, v133
	v_mul_f32_e32 v134, v9, v134
	v_mul_f32_e32 v135, v9, v135
	v_mul_f32_e32 v136, v9, v136
	v_mul_f32_e32 v137, v9, v137
	v_mul_f32_e32 v138, v9, v138
	v_mul_f32_e32 v139, v9, v139
	v_mul_f32_e32 v140, v9, v140
	v_mul_f32_e32 v141, v9, v141
	v_mul_f32_e32 v142, v9, v142
	v_mul_f32_e32 v143, v9, v143
	v_mul_f32_e32 v128, v10, v128
	v_mul_f32_e32 v129, v11, v129
	v_mul_f32_e32 v130, v12, v130
	v_mul_f32_e32 v131, v13, v131
	v_mul_f32_e32 v132, v14, v132
	v_mul_f32_e32 v133, v15, v133
	v_mul_f32_e32 v134, v16, v134
	v_mul_f32_e32 v135, v17, v135
	v_mul_f32_e32 v136, v18, v136
	v_mul_f32_e32 v137, v19, v137
	v_mul_f32_e32 v138, v20, v138
	v_mul_f32_e32 v139, v21, v139
	v_mul_f32_e32 v140, v22, v140
	v_mul_f32_e32 v141, v23, v141
	v_mul_f32_e32 v142, v24, v142
	v_mul_f32_e32 v143, v25, v143
	s_lshl_b32 s17, s16, 12
	s_add_u32 s18, s66, s17
	s_addc_u32 s19, s67, 0
	global_store_dwordx4 v0, v[128:131], s[18:19] nt
	global_store_dwordx4 v0, v[132:135], s[18:19] offset:1024 nt
	global_store_dwordx4 v0, v[136:139], s[18:19] offset:2048 nt
	global_store_dwordx4 v0, v[140:143], s[18:19] offset:3072 nt
	s_add_i32 s16, s16, s58
	s_waitcnt vmcnt(16)
	v_add_f32_e32 v80, v80, v81
	v_add_f32_e32 v82, v82, v83
	v_add_f32_e32 v84, v84, v85
	v_add_f32_e32 v86, v86, v87
	v_add_f32_e32 v88, v88, v89
	v_add_f32_e32 v90, v90, v91
	v_add_f32_e32 v92, v92, v93
	v_add_f32_e32 v94, v94, v95
	v_add_f32_e32 v80, v80, v82
	v_add_f32_e32 v84, v84, v86
	v_add_f32_e32 v88, v88, v90
	v_add_f32_e32 v92, v92, v94
	v_add_f32_e32 v80, v80, v84
	v_add_f32_e32 v88, v88, v92
	v_add_f32_e32 v80, v80, v88
	v_fmamk_f32 v80, v80, 0x3a800000, v8
	v_rsq_f32_e32 v9, v80
	v_lshlrev_b32_e32 v128, 16, v96
	v_and_b32_e32 v129, 0xffff0000, v96
	v_lshlrev_b32_e32 v130, 16, v97
	v_and_b32_e32 v131, 0xffff0000, v97
	v_lshlrev_b32_e32 v132, 16, v98
	v_and_b32_e32 v133, 0xffff0000, v98
	v_lshlrev_b32_e32 v134, 16, v99
	v_and_b32_e32 v135, 0xffff0000, v99
	v_lshlrev_b32_e32 v136, 16, v100
	v_and_b32_e32 v137, 0xffff0000, v100
	v_lshlrev_b32_e32 v138, 16, v101
	v_and_b32_e32 v139, 0xffff0000, v101
	v_lshlrev_b32_e32 v140, 16, v102
	v_and_b32_e32 v141, 0xffff0000, v102
	v_lshlrev_b32_e32 v142, 16, v103
	v_and_b32_e32 v143, 0xffff0000, v103
	v_mul_f32_e32 v128, v9, v128
	v_mul_f32_e32 v129, v9, v129
	v_mul_f32_e32 v130, v9, v130
	v_mul_f32_e32 v131, v9, v131
	v_mul_f32_e32 v132, v9, v132
	v_mul_f32_e32 v133, v9, v133
	v_mul_f32_e32 v134, v9, v134
	v_mul_f32_e32 v135, v9, v135
	v_mul_f32_e32 v136, v9, v136
	v_mul_f32_e32 v137, v9, v137
	v_mul_f32_e32 v138, v9, v138
	v_mul_f32_e32 v139, v9, v139
	v_mul_f32_e32 v140, v9, v140
	v_mul_f32_e32 v141, v9, v141
	v_mul_f32_e32 v142, v9, v142
	v_mul_f32_e32 v143, v9, v143
	v_mul_f32_e32 v128, v10, v128
	v_mul_f32_e32 v129, v11, v129
	v_mul_f32_e32 v130, v12, v130
	v_mul_f32_e32 v131, v13, v131
	v_mul_f32_e32 v132, v14, v132
	v_mul_f32_e32 v133, v15, v133
	v_mul_f32_e32 v134, v16, v134
	v_mul_f32_e32 v135, v17, v135
	v_mul_f32_e32 v136, v18, v136
	v_mul_f32_e32 v137, v19, v137
	v_mul_f32_e32 v138, v20, v138
	v_mul_f32_e32 v139, v21, v139
	v_mul_f32_e32 v140, v22, v140
	v_mul_f32_e32 v141, v23, v141
	v_mul_f32_e32 v142, v24, v142
	v_mul_f32_e32 v143, v25, v143
	s_lshl_b32 s17, s16, 12
	s_add_u32 s18, s66, s17
	s_addc_u32 s19, s67, 0
	global_store_dwordx4 v0, v[128:131], s[18:19] nt
	global_store_dwordx4 v0, v[132:135], s[18:19] offset:1024 nt
	global_store_dwordx4 v0, v[136:139], s[18:19] offset:2048 nt
	global_store_dwordx4 v0, v[140:143], s[18:19] offset:3072 nt
	s_add_i32 s16, s16, s58
	s_waitcnt vmcnt(12)
; __device__ __forceinline__ float row_rstd(const float* ss, int row) {
;     ...
;     const float s = (((a[0] + a[1]) + (a[2] + a[3])) + ((b[0] + b[1]) + (b[2] + b[3]))) + (((c[0] + c[1]) + (c[2] + c[3])) + ((d[0] + d[1]) + (d[2] + d[3])));
;     return __builtin_amdgcn_rsqf(s * (1.f / DM) + EPS);
; __global__ void __launch_bounds__(NWAVES * 64, 2) mk_fwd(Args args) {
;     ...
;         for (int m = gw; m < MT; m += NGW) { const float rs = row_rstd(ss, m);
;             const u32x4* xr = (const u32x4*)(X3 + (size_t)m * DM) + lane; f32x4* orow = (f32x4*)(P.out + (size_t)m * DM); const f32x4* gr = (const f32x4*)P.g_fin;
; #pragma unroll
;             for (int j = 0; j < 2; ++j) { const u32x4 w = xr[64 * j]; const int c4 = (64 * j + lane) * 2; const f32x4 ga = gr[c4], gb = gr[c4 + 1];
;                 f32x4 a, b2; a[0] = bflo(w.x) * rs * ga[0]; a[1] = bfhi(w.x) * rs * ga[1]; a[2] = bflo(w.y) * rs * ga[2]; a[3] = bfhi(w.y) * rs * ga[3];
;                 b2[0] = bflo(w.z) * rs * gb[0]; b2[1] = bfhi(w.z) * rs * gb[1]; b2[2] = bflo(w.w) * rs * gb[2]; b2[3] = bfhi(w.w) * rs * gb[3];
;                 orow[c4] = a; orow[c4 + 1] = b2; } }
	v_add_f32_e32 v104, v104, v105
	v_add_f32_e32 v106, v106, v107
	v_add_f32_e32 v108, v108, v109
	v_add_f32_e32 v110, v110, v111
	v_add_f32_e32 v112, v112, v113
	v_add_f32_e32 v114, v114, v115
	v_add_f32_e32 v116, v116, v117
	v_add_f32_e32 v118, v118, v119
	v_add_f32_e32 v104, v104, v106
	v_add_f32_e32 v108, v108, v110
	v_add_f32_e32 v112, v112, v114
	v_add_f32_e32 v116, v116, v118
	v_add_f32_e32 v104, v104, v108
	v_add_f32_e32 v112, v112, v116
	v_add_f32_e32 v104, v104, v112
	v_fmamk_f32 v104, v104, 0x3a800000, v8
	v_rsq_f32_e32 v9, v104
	v_lshlrev_b32_e32 v128, 16, v120
	v_and_b32_e32 v129, 0xffff0000, v120
	v_lshlrev_b32_e32 v130, 16, v121
	v_and_b32_e32 v131, 0xffff0000, v121
	v_lshlrev_b32_e32 v132, 16, v122
	v_and_b32_e32 v133, 0xffff0000, v122
	v_lshlrev_b32_e32 v134, 16, v123
	v_and_b32_e32 v135, 0xffff0000, v123
	v_lshlrev_b32_e32 v136, 16, v124
	v_and_b32_e32 v137, 0xffff0000, v124
	v_lshlrev_b32_e32 v138, 16, v125
	v_and_b32_e32 v139, 0xffff0000, v125
	v_lshlrev_b32_e32 v140, 16, v126
	v_and_b32_e32 v141, 0xffff0000, v126
	v_lshlrev_b32_e32 v142, 16, v127
	v_and_b32_e32 v143, 0xffff0000, v127
	v_mul_f32_e32 v128, v9, v128
	v_mul_f32_e32 v129, v9, v129
	v_mul_f32_e32 v130, v9, v130
	v_mul_f32_e32 v131, v9, v131
	v_mul_f32_e32 v132, v9, v132
	v_mul_f32_e32 v133, v9, v133
	v_mul_f32_e32 v134, v9, v134
	v_mul_f32_e32 v135, v9, v135
	v_mul_f32_e32 v136, v9, v136
	v_mul_f32_e32 v137, v9, v137
	v_mul_f32_e32 v138, v9, v138
	v_mul_f32_e32 v139, v9, v139
	v_mul_f32_e32 v140, v9, v140
	v_mul_f32_e32 v141, v9, v141
	v_mul_f32_e32 v142, v9, v142
	v_mul_f32_e32 v143, v9, v143
	v_mul_f32_e32 v128, v10, v128
	v_mul_f32_e32 v129, v11, v129
	v_mul_f32_e32 v130, v12, v130
	v_mul_f32_e32 v131, v13, v131
	v_mul_f32_e32 v132, v14, v132
	v_mul_f32_e32 v133, v15, v133
	v_mul_f32_e32 v134, v16, v134
	v_mul_f32_e32 v135, v17, v135
	v_mul_f32_e32 v136, v18, v136
	v_mul_f32_e32 v137, v19, v137
	v_mul_f32_e32 v138, v20, v138
	v_mul_f32_e32 v139, v21, v139
	v_mul_f32_e32 v140, v22, v140
	v_mul_f32_e32 v141, v23, v141
	v_mul_f32_e32 v142, v24, v142
	v_mul_f32_e32 v143, v25, v143
	s_lshl_b32 s17, s16, 12
	s_add_u32 s18, s66, s17
	s_addc_u32 s19, s67, 0
	global_store_dwordx4 v0, v[128:131], s[18:19] nt
	global_store_dwordx4 v0, v[132:135], s[18:19] offset:1024 nt
	global_store_dwordx4 v0, v[136:139], s[18:19] offset:2048 nt
	global_store_dwordx4 v0, v[140:143], s[18:19] offset:3072 nt
	s_lshl_b32 s17, s58, 2
	s_add_i32 s8, s8, s17
	s_mul_i32 s9, s58, 3
	s_add_i32 s9, s9, s8
	s_cmpk_lt_i32 s9, 0x4000
	s_cbranch_scc1 .Lp9_loop
